# P4: drains between the q / k_nope / v up-projection calls wait only for the DMA loads (vmcnt(16)), the last epilogue's stores stay in flight under the next call's prologue
# speedup vs baseline: 1.0156x; 1.0015x over previous
; #define PG8_WAIT_V(n) asm volatile("s_waitcnt vmcnt(" #n ")" ::: "memory")
; #define PG8_BAR __builtin_amdgcn_s_barrier()
; template <class Epi, class Sched, bool ALIGN_EPI = false, bool SP2 = false>
; __device__ __forceinline__ void gemm_phase(PG8_LAS unsigned char* lds, const Gemm g, const Sched& S, const Epi& E) {
;     ...
;     PG8_WAIT_V(0);
;     if constexpr (!ALIGN_EPI) { if (wr == 0) PG8_BAR; }
;     PG8_BAR;
.LBB0_416:
	s_waitcnt vmcnt(16)
	s_barrier
